# strategy 4: one static s_setprio 1 for waves 4-7 during the odd-layer attention loops (DSA + differential), reset at phase end
# baseline (speedup 1.0000x reference)
; #define LAS __attribute__((address_space(3)))
; __device__ __forceinline__ void dsa_attn_item(CParams& p, LAS unsigned char* lds, int b, int qb, int tid_in, int wave) {
;     ...
;     const int hd = wave & 3, qs = wave >> 2, r = lane & 31, hh = lane >> 5;
;     const int tb0 = b * SEQ; const int q0 = qb * 64 + 32 * qs;
;     for (int i = tid; i < 4 * 132; i += NTHREADS) bdl[i] = bd[i];
;     h16x8 qf[8];
; #pragma unroll
;     for (int s = 0; s < 8; ++s) qf[s] = *(const h16x8*)(proj + (size_t)(tb0 + q0 + r) * OD_N + 1536 + hd * 128 + 16 * s + 8 * hh);
;     f32x16 o[4];
; #pragma unroll
;     for (int d = 0; d < 4; ++d)
; #pragma unroll
;         for (int i = 0; i < 16; ++i) o[d][i] = 0.f;
;     float m_run = -INFINITY, l_run = 0.f;
;     const int qp = q0 + r;
;     const int vlo = r * 72 + ((hh ^ (r >> 3)) << 2), vhi = r * 72 + (((hh ^ (r >> 3)) ^ 2) << 2);
;     const unsigned long long* bmq = bm + (size_t)(tb0 + qp) * 64;
;     const LAS float* bdh = bdl + hd * 132;
;     const int nkt = qb + 1;
;     h16x8 pk[2], pv[2];
; #pragma unroll
;     for (int i = 0; i < 2; ++i) { const int key = i * 32 + (tid >> 4), ch = tid & 15;
;         pk[i] = *(const h16x8*)(proj + (size_t)(tb0 + key) * OD_N + 2048 + ch * 8);
;         pv[i] = *(const h16x8*)(proj + (size_t)(tb0 + key) * OD_N + 2176 + ch * 8); }
;     ATT_STAGE(0, 2048, 2176, 1);
;     unsigned long long mkn = bmq[0];
;     __syncthreads();
.LBB0_510:
	s_or_b64 exec, exec, s[4:5]
	v_readfirstlane_b32 s4, v16
	s_cmp_lt_u32 s4, 0x100
	s_cbranch_scc1 .Lprio_dsa
	s_setprio 1
.Lprio_dsa:
	v_add_u32_e32 v145, s84, v183
	v_and_b32_e32 v80, 31, v16
	v_add_u32_e32 v0, s58, v145
	v_bfe_u32 v81, v16, 5, 1
	v_or_b32_e32 v144, v80, v0
	v_mad_i64_i32 v[2:3], s[4:5], v144, s33, v[142:143]
	v_lshlrev_b32_e32 v0, 4, v81
	v_lshl_add_u64 v[34:35], v[2:3], 0, v[0:1]
	v_or_b32_e32 v0, v80, v145
	v_add_u32_e32 v14, s58, v0
	v_ashrrev_i32_e32 v17, 4, v16
	v_lshlrev_b32_e32 v0, 3, v16
	v_add_u32_e32 v147, s58, v17
	v_and_b32_e32 v0, 0x78, v0
	v_mov_b64_e32 v[36:37], s[14:15]
	v_mad_i64_i32 v[18:19], s[4:5], v147, s33, v[36:37]
	v_lshlrev_b32_e32 v0, 1, v0
	v_add_u32_e32 v22, 32, v147
	v_lshl_add_u64 v[18:19], v[18:19], 0, v[0:1]
	v_mad_i64_i32 v[22:23], s[4:5], v22, s33, v[36:37]
	v_add_co_u32_e32 v26, vcc, s3, v18
	s_min_i32 s4, s83, 1
	s_nop 0
	v_addc_co_u32_e32 v27, vcc, 0, v19, vcc
	v_lshl_add_u64 v[22:23], v[22:23], 0, v[0:1]
	v_lshl_add_u32 v40, s4, 6, v147
	v_add_co_u32_e32 v30, vcc, s3, v22
	v_mad_i64_i32 v[32:33], s[4:5], v40, s33, v[36:37]
	s_nop 0
	v_addc_co_u32_e32 v31, vcc, 0, v23, vcc
	v_lshl_add_u64 v[32:33], v[32:33], 0, v[0:1]
	v_add_u32_e32 v40, 32, v40
	v_add_co_u32_e32 v38, vcc, s3, v32
	v_mad_i64_i32 v[36:37], s[4:5], v40, s33, v[36:37]
	v_ashrrev_i32_e32 v15, 31, v14
	v_addc_co_u32_e32 v39, vcc, 0, v33, vcc
	v_lshl_add_u64 v[36:37], v[36:37], 0, v[0:1]
	global_load_dwordx4 v[2:5], v[34:35], off offset:3104
	global_load_dwordx4 v[6:9], v[34:35], off offset:3136
	global_load_dwordx4 v[10:13], v[34:35], off offset:3168
	global_load_dwordx4 v[96:99], v[34:35], off offset:3200
	global_load_dwordx4 v[100:103], v[34:35], off offset:3232
	global_load_dwordx4 v[104:107], v[34:35], off offset:3264
	v_lshlrev_b64 v[14:15], 9, v[14:15]
	global_load_dwordx4 v[108:111], v[34:35], off offset:3296
	global_load_dwordx4 v[18:21], v[26:27], off
	global_load_dwordx4 v[22:25], v[30:31], off
	s_nop 0
	global_load_dwordx4 v[26:29], v[26:27], off offset:256
	v_add_co_u32_e32 v36, vcc, 0x1000, v36
	v_lshl_add_u64 v[14:15], s[16:17], 0, v[14:15]
	global_load_dwordx4 v[30:33], v[30:31], off offset:256
	s_nop 0
	global_load_dwordx4 v[116:119], v[38:39], off
	v_addc_co_u32_e32 v37, vcc, 0, v37, vcc
	global_load_dwordx4 v[120:123], v[38:39], off offset:256
	global_load_dwordx4 v[128:131], v[36:37], off
	global_load_dwordx4 v[112:115], v[34:35], off offset:3072
	global_load_dwordx2 v[150:151], v[14:15], off
	global_load_dwordx4 v[124:127], v[36:37], off offset:256
	v_and_b32_e32 v16, 15, v16
	v_lshlrev_b32_e32 v34, 2, v16
	v_lshlrev_b32_e32 v35, 1, v17
	v_lshl_add_u32 v153, v16, 4, 0
	v_mul_u32_u24_e32 v155, 0x480, v16
	v_and_b32_e32 v16, 6, v35
	v_bfe_u32 v36, v17, 2, 1
	v_bfe_u32 v37, v17, 3, 1
	v_and_b32_e32 v38, -13, v17
	v_lshl_or_b32 v38, v36, 3, v38
	v_lshl_or_b32 v38, v37, 2, v38
	v_and_b32_e32 v34, 0x38, v34
	v_bitop3_b32 v36, v38, v34, -4 bitop3:0x6c
	v_mul_lo_u32 v154, v17, s97
	v_add_u32_e32 v162, 0, v16
	v_lshlrev_b32_e32 v163, 1, v36
	v_add_u32_e32 v35, v153, v154
	v_add3_u32 v16, v162, v163, v155
	s_mov_b64 s[4:5], -1
	s_cmp_gt_i32 s83, -1
	v_lshlrev_b32_e32 v152, 2, v81
	s_waitcnt vmcnt(9)
	ds_write_b128 v35, v[18:21]
	s_waitcnt vmcnt(7)
	ds_write_b16 v16, v26 offset:34816
	ds_write_b16_d16_hi v16, v26 offset:34960
	ds_write_b16 v16, v27 offset:35104
	ds_write_b16_d16_hi v16, v27 offset:35248
	ds_write_b16 v16, v28 offset:35392
	ds_write_b16_d16_hi v16, v28 offset:35536
	ds_write_b16 v16, v29 offset:35680
	ds_write_b16_d16_hi v16, v29 offset:35824
	v_add_u32_e32 v16, 32, v38
	v_bitop3_b32 v16, v16, v34, -4 bitop3:0x6c
	v_lshlrev_b32_e32 v164, 1, v16
	v_add3_u32 v16, v162, v164, v155
	ds_write_b128 v35, v[22:25] offset:8704
	s_waitcnt vmcnt(6)
	ds_write_b16 v16, v30 offset:34816
	ds_write_b16_d16_hi v16, v30 offset:34960
	ds_write_b16 v16, v31 offset:35104
	ds_write_b16_d16_hi v16, v31 offset:35248
	ds_write_b16 v16, v32 offset:35392
	ds_write_b16_d16_hi v16, v32 offset:35536
	ds_write_b16 v16, v33 offset:35680
	ds_write_b16_d16_hi v16, v33 offset:35824
	s_waitcnt lgkmcnt(0)
	s_barrier
	s_cbranch_scc0 .LBB0_591
	v_lshlrev_b32_e32 v146, 2, v81
	s_movk_i32 s4, 0x100
	v_lshlrev_b32_e64 v174, v146, s4
	s_movk_i32 s4, 0x200
	v_lshlrev_b32_e64 v175, v146, s4
	s_movk_i32 s4, 0x400
	v_lshlrev_b32_e64 v176, v146, s4
	s_movk_i32 s4, 0x800
	v_lshlrev_b32_e64 v177, v146, s4
	s_mov_b32 s4, 0x10000
	v_lshlrev_b32_e64 v178, v146, s4
	s_mov_b32 s4, 0x20000
	v_lshlrev_b32_e64 v179, v146, s4
	s_mov_b32 s4, 0x40000
	v_lshlrev_b32_e64 v180, v146, s4
	s_mov_b32 s4, 0x80000
	v_lshrrev_b32_e32 v16, 3, v80
	v_lshlrev_b32_e64 v181, v146, s4
	s_mov_b32 s4, 0x1000000
	v_xor_b32_e32 v16, v81, v16
	v_lshlrev_b32_e64 v192, v146, s4
	s_brev_b32 s4, 64
	v_lshlrev_b32_e32 v17, 2, v16
	v_lshrrev_b32_e32 v168, 4, v80
	v_xor_b32_e32 v168, v81, v168
	v_lshlrev_b32_e32 v168, 4, v168
	v_lshlrev_b32_e64 v193, v146, s4
	s_brev_b32 s4, 32
	v_add_u32_e32 v16, v145, v80
	v_mov_b32_e32 v30, v1
	v_mov_b32_e32 v31, v1
	v_xor_b32_e32 v165, 8, v17
	v_lshlrev_b32_e64 v194, v146, s4
	s_brev_b32 s4, 16
	v_sub_u32_e32 v196, v16, v146
	v_mov_b32_e32 v16, v1
	v_mov_b32_e32 v17, v1
	v_mov_b32_e32 v18, v1
	v_mov_b32_e32 v19, v1
	v_mov_b32_e32 v20, v1
	v_mov_b32_e32 v21, v1
	v_mov_b32_e32 v22, v1
	v_mov_b32_e32 v23, v1
	v_mov_b32_e32 v24, v1
	v_mov_b32_e32 v25, v1
	v_mov_b32_e32 v26, v1
	v_mov_b32_e32 v27, v1
	v_mov_b32_e32 v28, v1
	v_mov_b32_e32 v29, v1
	v_mov_b64_e32 v[46:47], v[30:31]
	v_mov_b64_e32 v[62:63], v[30:31]
	v_mov_b64_e32 v[78:79], v[30:31]
	s_mov_b32 s30, 2
	v_lshl_add_u32 v166, v81, 4, 0
	v_mad_u32_u24 v167, v80, s60, 0
	v_mul_u32_u24_e32 v169, 0x110, v80
	v_lshlrev_b32_e64 v170, v146, 1
	v_lshlrev_b32_e64 v171, v146, 2
	v_lshlrev_b32_e64 v172, v146, 4
	v_lshlrev_b32_e64 v173, v146, 8
	v_lshlrev_b32_e64 v195, v146, s4
	v_mov_b32_e32 v198, 0
	v_mov_b32_e32 v201, 0xff800000
	s_movk_i32 s31, 0xbf
	v_mov_b64_e32 v[44:45], v[28:29]
	v_mov_b64_e32 v[42:43], v[26:27]
	v_mov_b64_e32 v[40:41], v[24:25]
	v_mov_b64_e32 v[38:39], v[22:23]
	v_mov_b64_e32 v[36:37], v[20:21]
	v_mov_b64_e32 v[34:35], v[18:19]
	v_mov_b64_e32 v[32:33], v[16:17]
	v_mov_b64_e32 v[60:61], v[28:29]
	v_mov_b64_e32 v[58:59], v[26:27]
	v_mov_b64_e32 v[56:57], v[24:25]
	v_mov_b64_e32 v[54:55], v[22:23]
	v_mov_b64_e32 v[52:53], v[20:21]
	v_mov_b64_e32 v[50:51], v[18:19]
	v_mov_b64_e32 v[48:49], v[16:17]
	v_mov_b64_e32 v[76:77], v[28:29]
	v_mov_b64_e32 v[74:75], v[26:27]
	v_mov_b64_e32 v[72:73], v[24:25]
	v_mov_b64_e32 v[70:71], v[22:23]
	v_mov_b64_e32 v[68:69], v[20:21]
	v_mov_b64_e32 v[66:67], v[18:19]
	v_mov_b64_e32 v[64:65], v[16:17]

; __device__ __forceinline__ void diff_attn_item(CParams& p, int j, int layer, LAS unsigned char* lds, int b, int h, int qb, int tid_in, int lane_in, int wave) {
;     ...
;     const int mp = wave >> 2, qs = wave & 3, r = lane & 31, hh = lane >> 5;
;     const int tb0 = b * SEQ; const int q0 = qb * 128 + 32 * qs;
;     if (tid < 129) bdl[tid] = bd[tid];
;     h16x8 qf[4];
; #pragma unroll
;     for (int s = 0; s < 4; ++s) qf[s] = *(const h16x8*)(proj + (size_t)(tb0 + q0 + r) * OD_N + h * 128 + mp * 64 + 16 * s + 8 * hh);
;     f32x16 o[4];
; #pragma unroll
;     for (int d = 0; d < 4; ++d)
; #pragma unroll
;         for (int i = 0; i < 16; ++i) o[d][i] = 0.f;
;     float m_run = -INFINITY, l_run = 0.f;
;     const int qp = q0 + r;
;     const int vlo = r * 72 + ((hh ^ (r >> 3)) << 2), vhi = r * 72 + (((hh ^ (r >> 3)) ^ 2) << 2);
;     const int nkt = 2 * (qb + 1);
;     h16x8 pk[2], pv[2];
; #pragma unroll
;     for (int i = 0; i < 2; ++i) { const int key = i * 32 + (tid >> 4), ch = tid & 15;
;         pk[i] = *(const h16x8*)(proj + (size_t)(tb0 + key) * OD_N + 512 + h * 128 + ch * 8);
;         pv[i] = *(const h16x8*)(proj + (size_t)(tb0 + key) * OD_N + 1024 + h * 128 + ch * 8); }
;     ...
;     ATT_STAGE(0, 512 + h * 128, 1024 + h * 128, 1);
;     __syncthreads();
.LBB0_597:
	s_or_b64 exec, exec, s[4:5]
	v_readfirstlane_b32 s4, v161
	s_cmp_lt_u32 s4, 0x100
	s_cbranch_scc1 .Lprio_diff
	s_setprio 1
.Lprio_diff:
	s_lshl_b32 s4, s35, 2
	s_and_b32 s4, s4, 24
	s_add_i32 s4, s4, s73
	s_and_b32 s4, s4, 31
	s_and_b32 s5, s35, 1
	s_xor_b32 s6, s4, 31
	s_cmp_eq_u32 s5, 0
	s_cselect_b32 s6, s4, s6
	s_lshl_b32 s4, s35, 10
	s_and_b32 s4, s4, 0x1000
	s_or_b32 s7, s4, s34
	v_ashrrev_i32_e32 v3, 4, v2
	v_add_u32_e32 v200, s7, v3
	v_lshlrev_b32_e32 v0, 4, v2
	s_lshl_b32 s30, s6, 7
	v_mov_b64_e32 v[20:21], s[14:15]
	v_and_b32_e32 v22, 0xf0, v0
	v_add_u32_e32 v0, 32, v200
	v_and_b32_e32 v198, 31, v2
	v_or_b32_e32 v199, s30, v186
	s_lshl_b32 s58, s12, 8
	v_mad_i64_i32 v[4:5], s[4:5], v200, s33, v[20:21]
	v_mad_i64_i32 v[12:13], s[4:5], v0, s33, v[20:21]
	s_lshl_b32 s36, s12, 7
	s_lshl_b32 s37, s6, 1
	v_or3_b32 v0, s7, v198, v199
	s_add_u32 s4, s14, s58
	v_mad_u64_u32 v[20:21], s[12:13], v0, s33, v[20:21]
	v_bfe_u32 v30, v2, 5, 1
	s_addc_u32 s5, s15, 0
	v_lshl_add_u64 v[20:21], v[20:21], 0, s[58:59]
	v_lshl_add_u64 v[4:5], v[4:5], 0, s[58:59]
	v_mov_b32_e32 v23, v1
	v_lshl_add_u64 v[12:13], v[12:13], 0, s[58:59]
	v_mov_b32_e32 v25, v1
	v_lshlrev_b32_e32 v24, 4, v30
	v_add_u32_e32 v28, 64, v200
	v_add_u32_e32 v31, 0x60, v200
	v_mov_b64_e32 v[26:27], s[4:5]
	v_lshl_add_u64 v[20:21], v[140:141], 1, v[20:21]
	v_lshl_add_u64 v[8:9], v[4:5], 0, v[22:23]
	v_lshl_add_u64 v[16:17], v[12:13], 0, v[22:23]
	v_mad_i64_i32 v[28:29], s[12:13], v28, s33, v[26:27]
	v_mad_i64_i32 v[26:27], s[12:13], v31, s33, v[26:27]
	v_lshl_add_u64 v[20:21], v[20:21], 0, v[24:25]
	global_load_dwordx4 v[4:7], v[8:9], off offset:1024
	s_nop 0
	global_load_dwordx4 v[8:11], v[8:9], off offset:2048
	s_nop 0
	global_load_dwordx4 v[12:15], v[16:17], off offset:1024
	s_nop 0
	global_load_dwordx4 v[16:19], v[16:17], off offset:2048
	v_lshl_add_u64 v[28:29], v[28:29], 0, v[22:23]
	v_lshl_add_u64 v[26:27], v[26:27], 0, v[22:23]
	global_load_dwordx4 v[110:113], v[20:21], off
	global_load_dwordx4 v[106:109], v[20:21], off offset:32
	global_load_dwordx4 v[102:105], v[20:21], off offset:64
	global_load_dwordx4 v[98:101], v[20:21], off offset:96
	global_load_dwordx4 v[126:129], v[28:29], off offset:1024
	global_load_dwordx4 v[118:121], v[28:29], off offset:2048
	global_load_dwordx4 v[122:125], v[26:27], off offset:1024
	global_load_dwordx4 v[114:117], v[26:27], off offset:2048
	v_and_b32_e32 v193, 63, v2
	v_bfe_u32 v20, v2, 3, 2
	v_and_b32_e32 v2, 15, v2
	v_lshlrev_b32_e32 v21, 2, v2
	v_lshlrev_b32_e32 v25, 1, v3
	v_lshl_add_u32 v202, v2, 4, 0
	v_mul_lo_u32 v203, v3, s97
	v_mul_u32_u24_e32 v204, 0x480, v2
	v_and_b32_e32 v25, 6, v25
	v_bfe_u32 v26, v3, 2, 1
	v_bfe_u32 v27, v3, 3, 1
	v_and_b32_e32 v2, -13, v3
	v_lshl_or_b32 v2, v26, 3, v2
	v_lshl_or_b32 v26, v27, 2, v2
	v_and_b32_e32 v21, 0x38, v21
	v_add_u32_e32 v2, 32, v26
	v_bitop3_b32 v3, v26, v21, -4 bitop3:0x6c
	v_bitop3_b32 v2, v2, v21, -4 bitop3:0x6c
	v_add_u32_e32 v205, 0, v25
	v_lshlrev_b32_e32 v206, 1, v3
	v_add_u32_e32 v27, v202, v203
	v_lshlrev_b32_e32 v207, 1, v2
	v_add3_u32 v2, v205, v206, v204
	v_xor_b32_e32 v20, v30, v20
	v_lshlrev_b32_e32 v26, 2, v20
	v_lshlrev_b32_e32 v192, 2, v30
	v_xor_b32_e32 v194, 8, v26
	v_add_u32_e32 v208, v187, v24
	v_bfe_u32 v196, v193, 4, 1
	v_xor_b32_e32 v196, v30, v196
	v_lshlrev_b32_e32 v196, 4, v196
	s_waitcnt vmcnt(29)
	v_lshl_add_u64 v[130:131], s[4:5], 0, v[22:23]
	v_mov_b32_e32 v3, v1
	s_mov_b32 s38, 0
	s_or_b32 s39, s37, 1
	v_or_b32_e32 v210, 31, v199
	v_mad_u32_u24 v195, v198, s60, 0
	v_mul_u32_u24_e32 v209, 0x110, v198
	v_mad_u32_u24 v211, v198, s97, v208
	v_mov_b32_e32 v197, 0
	v_mov_b32_e32 v201, 0xff800000
	s_movk_i32 s40, 0xbf
	s_waitcnt vmcnt(11)
	ds_write_b128 v27, v[4:7]
	s_waitcnt vmcnt(10)
	ds_write_b16 v2, v8 offset:34816
	ds_write_b16_d16_hi v2, v8 offset:34960
	ds_write_b16 v2, v9 offset:35104
	ds_write_b16_d16_hi v2, v9 offset:35248
	ds_write_b16 v2, v10 offset:35392
	ds_write_b16_d16_hi v2, v10 offset:35536
	ds_write_b16 v2, v11 offset:35680
	ds_write_b16_d16_hi v2, v11 offset:35824
	s_waitcnt vmcnt(9)
	ds_write_b128 v27, v[12:15] offset:8704
	v_add3_u32 v2, v205, v207, v204
	s_waitcnt vmcnt(8)
	ds_write_b16 v2, v16 offset:34816
	ds_write_b16_d16_hi v2, v16 offset:34960
	ds_write_b16 v2, v17 offset:35104
	ds_write_b16_d16_hi v2, v17 offset:35248
	ds_write_b16 v2, v18 offset:35392
	ds_write_b16_d16_hi v2, v18 offset:35536
	ds_write_b16 v2, v19 offset:35680
	ds_write_b16_d16_hi v2, v19 offset:35824
	v_add3_u32 v2, v191, s30, v198
	v_mov_b32_e32 v16, v1
	v_mov_b32_e32 v17, v1
	v_sub_u32_e32 v212, v2, v192
	v_mov_b32_e32 v2, v1
	v_mov_b32_e32 v4, v1
	v_mov_b32_e32 v5, v1
	v_mov_b32_e32 v6, v1
	v_mov_b32_e32 v7, v1
	v_mov_b32_e32 v8, v1
	v_mov_b32_e32 v9, v1
	v_mov_b32_e32 v10, v1
	v_mov_b32_e32 v11, v1
	v_mov_b32_e32 v12, v1
	v_mov_b32_e32 v13, v1
	v_mov_b32_e32 v14, v1
	v_mov_b32_e32 v15, v1
	v_mov_b64_e32 v[32:33], v[16:17]
	v_mov_b64_e32 v[48:49], v[16:17]
	v_mov_b64_e32 v[64:65], v[16:17]
	v_mov_b64_e32 v[30:31], v[14:15]
	v_mov_b64_e32 v[28:29], v[12:13]
	v_mov_b64_e32 v[26:27], v[10:11]
	v_mov_b64_e32 v[24:25], v[8:9]
	v_mov_b64_e32 v[22:23], v[6:7]
	v_mov_b64_e32 v[20:21], v[4:5]
	v_mov_b64_e32 v[18:19], v[2:3]
	v_mov_b64_e32 v[46:47], v[14:15]
	v_mov_b64_e32 v[44:45], v[12:13]
	v_mov_b64_e32 v[42:43], v[10:11]
	v_mov_b64_e32 v[40:41], v[8:9]
	v_mov_b64_e32 v[38:39], v[6:7]
	v_mov_b64_e32 v[36:37], v[4:5]
	v_mov_b64_e32 v[34:35], v[2:3]
	v_mov_b64_e32 v[62:63], v[14:15]
	v_mov_b64_e32 v[60:61], v[12:13]
	v_mov_b64_e32 v[58:59], v[10:11]
	v_mov_b64_e32 v[56:57], v[8:9]
	v_mov_b64_e32 v[54:55], v[6:7]
	v_mov_b64_e32 v[52:53], v[4:5]
	v_mov_b64_e32 v[50:51], v[2:3]
	s_waitcnt lgkmcnt(0)
	s_barrier

; __device__ __forceinline__ void grid_barrier(unsigned* ctr, unsigned gen, const int wid_s) {
;     __syncthreads();
;     if (TIDX == 0) {
;         __builtin_amdgcn_fence(__ATOMIC_RELEASE, "agent");
;         asm volatile("s_waitcnt vmcnt(0)" ::: "memory");
;         const unsigned target = gen * gridDim.x;
;         __hip_atomic_fetch_add(ctr, 1u, __ATOMIC_RELAXED, __HIP_MEMORY_SCOPE_AGENT);
;         unsigned spins = 0;
;         while (__hip_atomic_load(ctr, __ATOMIC_RELAXED, __HIP_MEMORY_SCOPE_AGENT) < target) { __builtin_amdgcn_s_sleep(1); if (++spins > (1u << 24)) break; }
.LBB0_748:
	s_setprio 0
	s_add_i32 s28, s71, 2
	v_readlane_b32 s4, v253, 4
	s_cmp_ge_i32 s28, s4
	s_cbranch_scc1 .LBB0_780
	v_readlane_b32 s4, v252, 43
	s_cmp_lg_u32 s4, 0
	s_cbranch_scc0 .LBB0_766
	v_readlane_b32 s8, v253, 1
	v_sub_u32_e32 v0, 0, v218
	v_readlane_b32 s4, v252, 3
	v_readlane_b32 s9, v253, 2
	s_waitcnt lgkmcnt(0)
	v_cmp_eq_u32_e32 vcc, s4, v0
	s_barrier
	s_and_saveexec_b64 s[4:5], vcc
	s_cbranch_execz .LBB0_768
	s_load_dwordx2 s[8:9], s[8:9], 0xc8
	s_mov_b64 s[10:11], exec
	buffer_wbl2 sc1
	s_waitcnt vmcnt(0) lgkmcnt(0)
	s_waitcnt vmcnt(0)
	v_mbcnt_lo_u32_b32 v0, s10, 0
	s_add_u32 s8, s8, 0xe781100
	v_mbcnt_hi_u32_b32 v0, s11, v0
	s_addc_u32 s9, s9, 0
	v_cmp_eq_u32_e32 vcc, 0, v0
	s_and_saveexec_b64 s[12:13], vcc
	s_cbranch_execz .LBB0_753
	s_bcnt1_i32_b64 s6, s[10:11]
	v_mov_b32_e32 v0, s6
	global_atomic_add v1, v0, s[8:9]
